# P2/P11 4x8 tile rounds, M-tile groups visited most-recently-written first
# baseline (speedup 1.0000x reference)
.LBB0_362:
	s_add_i32 s2, s6, s2
	s_lshr_b32 s5, s2, 5
	s_and_b32 s2, s2, 31
	s_lshl_b32 s5, s5, 2
	s_and_b32 s3, s2, 3
	s_add_i32 s79, s5, s3
	s_xor_b32 s79, s79, 12
	s_lshr_b32 s80, s2, 2
	s_andn2_b64 vcc, exec, s[0:1]
	s_cbranch_vccnz .LBB0_357

.LBB0_373:
	s_ashr_i32 s10, s42, 3
	s_add_i32 s10, s54, s10
	s_lshr_b32 s42, s10, 5
	s_lshl_b32 s42, s42, 2
	s_and_b32 s10, s10, 31
	s_lshr_b32 s77, s10, 2
	s_and_b32 s10, s10, 3
	s_add_i32 s78, s42, s10
	s_xor_b32 s78, s78, 12

.LBB0_1550:
	v_lshrrev_b32_e32 v4, 1, v0
	v_lshrrev_b32_e32 v5, 5, v0
	v_lshlrev_b32_e32 v1, 4, v0
	v_and_b32_e32 v2, 32, v0
	v_and_b32_e32 v4, 24, v4
	v_and_b32_e32 v5, 4, v5
	v_bfe_u32 v6, v0, 2, 2
	v_bfe_u32 v3, v0, 2, 4
	v_bitop3_b32 v1, v1, v2, 48 bitop3:0x6c
	v_and_b32_e32 v10, 64, v0
	v_or3_b32 v4, v5, v6, v4
	v_lshrrev_b32_e32 v5, 3, v0
	v_or_b32_e32 v2, v1, v10
	v_and_or_b32 v6, v5, 48, v3
	v_and_or_b32 v5, v5, 32, v4
	v_lshrrev_b32_e32 v2, 1, v2
	v_mul_u32_u24_e32 v5, 0x1600, v5
	s_add_u32 s22, s26, 0x11c00000
	v_or_b32_e32 v5, v5, v2
	s_addc_u32 s23, s27, 0
	v_lshlrev_b32_e32 v130, 1, v5
	v_bfe_u32 v5, v0, 3, 25
	s_add_u32 s24, s26, 0x2d00000
	v_or_b32_e32 v5, 64, v5
	s_movk_i32 s1, 0x70
	s_addc_u32 s28, s27, 0
	v_and_or_b32 v3, v5, s1, v3
	s_movk_i32 s1, 0x60
	s_add_i32 s0, s4, s0
	v_and_or_b32 v4, v5, s1, v4
	s_lshr_b32 s6, s0, 5
	s_lshl_b32 s6, s6, 2
	s_and_b32 s7, s0, 28
	s_lshl_b32 s7, s7, 1
	s_and_b32 s0, s0, 3
	s_lshr_b32 s5, s2, 6
	s_add_i32 s44, s6, s0
	s_xor_b32 s44, s44, 12
	s_ashr_i32 s0, s7, 3
	s_lshr_b32 s3, s2, 8
	s_lshl_b32 s29, s5, 10
	s_lshr_b32 s4, s7, 3
	s_mul_hi_i32 s1, s0, 0x2c0000
	s_mul_i32 s0, s0, 0x2c0000
	v_mul_u32_u24_e32 v12, 0x1600, v3
	s_add_u32 s20, s24, s0
	v_or_b32_e32 v3, v12, v2
	s_addc_u32 s21, s28, s1
	s_add_i32 s30, s29, 0
	v_mul_u32_u24_e32 v11, 0x1600, v6
	v_lshlrev_b32_e32 v132, 1, v3
	v_mul_u32_u24_e32 v3, 0x1600, v4
	s_add_i32 m0, s30, 0x10000
	v_or_b32_e32 v6, v2, v11
	v_or_b32_e32 v2, v3, v2
	global_load_lds_dwordx4 v130, s[20:21]
	s_add_i32 m0, s30, 0x12000
	v_lshlrev_b32_e32 v134, 1, v2
	s_add_u32 s0, s20, 0x160000
	global_load_lds_dwordx4 v134, s[20:21]
	s_addc_u32 s1, s21, 0
	s_add_i32 m0, s30, 0x14000
	s_mul_i32 s8, s44, 0x2c0000
	global_load_lds_dwordx4 v130, s[0:1]
	s_add_i32 m0, s30, 0x16000
	s_mul_hi_i32 s6, s44, 0x2c0000
	s_add_u32 s16, s22, s8
	s_addc_u32 s17, s23, s6
	s_add_i32 s31, s30, 0x2000
	v_lshlrev_b32_e32 v128, 1, v6
	global_load_lds_dwordx4 v134, s[0:1]
	s_mov_b32 m0, s30
	s_add_u32 s0, s16, 0x160000
	global_load_lds_dwordx4 v128, s[16:17]
	s_mov_b32 m0, s31
	s_addc_u32 s1, s17, 0
	s_add_i32 s34, s30, 0x4000
	global_load_lds_dwordx4 v132, s[16:17]
	s_mov_b32 m0, s34
	s_add_i32 s35, s30, 0x6000
	global_load_lds_dwordx4 v128, s[0:1]
	s_mov_b32 m0, s35
	v_mov_b32_e32 v131, 0
	global_load_lds_dwordx4 v132, s[0:1]
	v_mov_b32_e32 v135, v131
	v_mov_b32_e32 v129, v131
	v_mov_b32_e32 v133, v131
	s_cmp_eq_u32 s3, 1
	s_mov_b32 s36, 0
	v_lshl_add_u64 v[8:9], s[20:21], 0, v[130:131]
	v_lshl_add_u64 v[6:7], s[20:21], 0, v[134:135]
	v_lshl_add_u64 v[2:3], s[16:17], 0, v[128:129]
	s_cselect_b64 s[0:1], -1, 0
	s_cmp_lg_u32 s3, 1
	v_lshl_add_u64 v[4:5], s[16:17], 0, v[132:133]
	s_cbranch_scc1 .LBB0_1552
	s_barrier

.LBB0_1560:
	s_ashr_i32 s2, s14, 3
	s_add_i32 s2, s26, s2
	s_lshr_b32 s14, s2, 5
	s_lshl_b32 s14, s14, 2
	s_and_b32 s2, s2, 31
	s_lshr_b32 s42, s2, 2
	s_and_b32 s2, s2, 3
	s_add_i32 s43, s14, s2
	s_xor_b32 s43, s43, 12
